# MLA K/V staging via LDS-DMA with a 3-slot ring, tiles prefetched two ahead (tail waits only for tile t+1); barrier state words saved/restored around slot 2
# baseline (speedup 1.0000x reference)
.LBB0_779:
	s_or_b64 exec, exec, s[0:1]
	v_mov_b32_e32 v157, 0x20400
	ds_read_b32 v215, v157
	s_waitcnt lgkmcnt(0)
	v_readfirstlane_b32 s33, v215
	s_nop 3
	v_writelane_b32 v254, s33, 59
	ds_read_b32 v215, v157 offset:4
	s_waitcnt lgkmcnt(0)
	v_readfirstlane_b32 s33, v215
	s_nop 3
	v_writelane_b32 v254, s33, 60
	ds_read_b32 v215, v157 offset:8
	s_waitcnt lgkmcnt(0)
	v_readfirstlane_b32 s33, v215
	s_nop 3
	v_writelane_b32 v254, s33, 61
	ds_read_b32 v215, v157 offset:12
	s_waitcnt lgkmcnt(0)
	v_readfirstlane_b32 s33, v215
	s_nop 3
	v_writelane_b32 v254, s33, 62
	s_add_i32 s33, 0, 0x1f040
	s_mov_b32 s28, 0x3c800000
	s_waitcnt lgkmcnt(0)
	v_and_b32_e32 v0, 64, v213
	s_mov_b32 s27, 0
	v_mov_b32_e32 v157, 0
	v_mov_b32_e32 v215, s33
	s_movk_i32 s37, 0x300
	s_movk_i32 s42, 0x1200
	s_movk_i32 s43, 0xc00
	s_movk_i32 s44, 0x190
	s_movk_i32 s45, 0xffb0
	s_brev_b32 s29, 60
	s_mov_b32 s46, 0x800000
	s_mov_b32 s36, 0x3dd53b94
	s_movk_i32 s47, 0x2000
	s_mov_b32 s48, 0x41000000
	s_movk_i32 s49, 0x1e00
	v_xor_b32_e32 v159, 32, v213
	v_add_u32_e32 v214, 64, v0
	v_mov_b32_e32 v158, 0x358637bd
	v_mov_b32_e32 v216, 0xff800000
	s_barrier
	s_branch .LBB0_782

.LBB0_791:
	s_cmp_eq_u32 s101, 0
	s_cbranch_scc1 .Ldma_w0
	s_cmp_gt_u32 s13, 4
	s_cbranch_scc1 .Ldma_w5
	s_waitcnt vmcnt(6)
	s_branch .Ldma_wd
.Ldma_w5:
	s_waitcnt vmcnt(5)
	s_branch .Ldma_wd

.Ldma_wd:
	s_add_i32 s26, s57, 1
	s_cmp_lg_u32 s26, 3
	s_cselect_b32 s57, s26, 0
	s_add_i32 s53, s53, 64
	s_add_i32 s56, s56, 1
	s_cmp_lg_u32 s55, s56
	s_waitcnt lgkmcnt(0)
	s_barrier
	s_cbranch_scc0 .LBB0_780
.LBB0_792:
	s_mov_b32 s101, 0
	s_cmp_lg_u32 s56, 0xffffff80
	s_cbranch_scc1 .Ldma_nf
	s_add_i32 s26, s56, 0x81
	s_cmp_ge_u32 s26, s52
	s_cbranch_scc1 .Ldma_nf
	s_mov_b32 s58, 1
	s_lshl_b32 s59, s13, 10
	s_add_i32 s26, s59, 0xb400
	v_mad_u64_u32 v[138:139], s[60:61], v132, s58, v[120:121]
	s_mov_b32 m0, s26
	s_nop 0
	global_load_lds_dwordx4 v[138:139], off
	v_mad_u64_u32 v[162:163], s[60:61], v133, s58, v[122:123]
	s_add_i32 m0, s26, 0x2000
	s_nop 0
	global_load_lds_dwordx4 v[162:163], off
	v_mad_u64_u32 v[138:139], s[60:61], v134, s58, v[124:125]
	s_add_i32 m0, s26, 0x4000
	s_nop 0
	global_load_lds_dwordx4 v[138:139], off
	v_mad_u64_u32 v[162:163], s[60:61], v135, s58, v[126:127]
	s_add_i32 m0, s26, 0x6000
	s_nop 0
	global_load_lds_dwordx4 v[162:163], off
	v_mad_u64_u32 v[138:139], s[60:61], v136, s58, v[128:129]
	s_add_i32 m0, s26, 0x8000
	s_nop 0
	global_load_lds_dwordx4 v[138:139], off
	s_cmp_gt_u32 s13, 4
	s_cbranch_scc1 .Ldma_skip5a
	v_mad_u64_u32 v[162:163], s[60:61], v137, s58, v[130:131]
	s_add_i32 m0, s26, 0xa000
	s_nop 0
	global_load_lds_dwordx4 v[162:163], off
.Ldma_skip5a:
.Ldma_nf:
	s_add_i32 s26, s56, 0x82
	s_cmp_ge_u32 s26, s52
	s_cbranch_scc1 .LBB0_796
	s_lshr_b32 s58, s53, 6
	s_add_i32 s58, s58, 2
	s_add_i32 s26, s57, 2
	s_cmp_ge_u32 s26, 3
	s_cselect_b32 s59, 3, 0
	s_sub_i32 s26, s26, s59
	s_mul_i32 s26, s26, 0xb400
	s_lshl_b32 s59, s13, 10
	s_add_i32 s26, s26, s59
	s_mov_b32 s101, 1
	v_mad_u64_u32 v[138:139], s[60:61], v132, s58, v[120:121]
	s_mov_b32 m0, s26
	s_nop 0
	global_load_lds_dwordx4 v[138:139], off
	v_mad_u64_u32 v[162:163], s[60:61], v133, s58, v[122:123]
	s_add_i32 m0, s26, 0x2000
	s_nop 0
	global_load_lds_dwordx4 v[162:163], off
	v_mad_u64_u32 v[138:139], s[60:61], v134, s58, v[124:125]
	s_add_i32 m0, s26, 0x4000
	s_nop 0
	global_load_lds_dwordx4 v[138:139], off
	v_mad_u64_u32 v[162:163], s[60:61], v135, s58, v[126:127]
	s_add_i32 m0, s26, 0x6000
	s_nop 0
	global_load_lds_dwordx4 v[162:163], off
	v_mad_u64_u32 v[138:139], s[60:61], v136, s58, v[128:129]
	s_add_i32 m0, s26, 0x8000
	s_nop 0
	global_load_lds_dwordx4 v[138:139], off
	s_cmp_gt_u32 s13, 4
	s_cbranch_scc1 .Ldma_skip5b
	v_mad_u64_u32 v[162:163], s[60:61], v137, s58, v[130:131]
	s_add_i32 m0, s26, 0xa000
	s_nop 0
	global_load_lds_dwordx4 v[162:163], off

.LBB0_807:
	v_mov_b32_e32 v121, 0x20400
	v_readlane_b32 s33, v254, 59
	s_nop 3
	v_mov_b32_e32 v136, s33
	s_nop 1
	ds_write_b32 v121, v136
	s_waitcnt lgkmcnt(0)
	v_readlane_b32 s33, v254, 60
	s_nop 3
	v_mov_b32_e32 v136, s33
	s_nop 1
	ds_write_b32 v121, v136 offset:4
	s_waitcnt lgkmcnt(0)
	v_readlane_b32 s33, v254, 61
	s_nop 3
	v_mov_b32_e32 v136, s33
	s_nop 1
	ds_write_b32 v121, v136 offset:8
	s_waitcnt lgkmcnt(0)
	v_readlane_b32 s33, v254, 62
	s_nop 3
	v_mov_b32_e32 v136, s33
	s_nop 1
	ds_write_b32 v121, v136 offset:12
	s_waitcnt lgkmcnt(0)
	s_add_i32 s33, 0, 0x1f040
	s_mov_b32 s5, 0
	v_mov_b32_e32 v121, 0
	v_mov_b32_e32 v136, s33
	s_movk_i32 s40, 0xff
	s_movk_i32 s41, 0xf00
	s_mov_b64 s[8:9], 0x1600
	s_movk_i32 s42, 0x1000
	s_movk_i32 s43, 0xffc0
	s_movk_i32 s44, 0x43f
	s_mov_b32 s45, 0xcccccccd
	s_movk_i32 s46, 0xffec
	s_mov_b32 s47, 0x78787879
	s_movk_i32 s48, 0xffef
	s_mov_b64 s[12:13], 0x20000
	v_mov_b32_e32 v137, 0x358637bd
	s_mov_b32 s49, 0x800000
	s_mov_b64 s[16:17], 0x40000
	s_mov_b32 s50, 0x41000000
	s_mov_b64 s[18:19], 0x1a00
	s_mov_b64 s[26:27], 0x17000c00
	s_mov_b32 s51, 0x17000000
	s_branch .LBB0_810
